# GDN chunk outputs: LDS operands for both 16-token blocks prefetched, two MFMA chains interleaved
# baseline (speedup 1.0000x reference)
; #define MFMA16F(a, b, c) __builtin_amdgcn_mfma_f32_16x16x4f32((a), (b), (c), 0, 0, 0)
; DI void gdn_scan_block(LAS unsigned char* lds, int c, const float* P, const GdnPar& pr, float* ORAW, int tid, int lane, int wave) {
;     ...
;             for (int tb = 0; tb < 2; ++tb) { f32x4 o;
; #pragma unroll
;                 for (int i = 0; i < 4; ++i) o[i] = PQa[tb][i] * __expf(GC_[16 * tb + 4 * g + i]);
; #pragma unroll
;                 for (int js = 0; js < 8; ++js) o = MFMA16F(M2[(16 * tb + m) * 33 + 4 * js + g], bC[js], o);
; #pragma unroll
;                 for (int i = 0; i < 4; ++i) ORAW[(tok_base + cidx * 32 + 16 * tb + 4 * g + i) * MIXW + vh * 128 + half * 64 + cw16 + m] = o[i]; }
;             const float e31 = __expf(GC_[31]);
;             float ej[8];
; #pragma unroll
;             for (int js = 0; js < 8; ++js) ej[js] = E31_[4 * js + g];
; #pragma unroll
;             for (int kb8 = 0; kb8 < 8; ++kb8) { f32x4 acc = Sacc[kb8] * e31;
; #pragma unroll
;                 for (int js = 0; js < 8; ++js) acc = MFMA16F(K_[(4 * js + g) * KP + 16 * kb8 + m] * ej[js], bC[js], acc);
;                 Sacc[kb8] = acc; }
.LBB0_888:
	s_or_b64 exec, exec, s[34:35]
	s_waitcnt lgkmcnt(0)
	v_add_u32_e32 v106, 0xd400, v186
	v_add_u32_e32 v128, 0xdc00, v186
	ds_read2st64_b32 v[78:79], v134 offset1:4
	ds_read2st64_b32 v[76:77], v134 offset0:8 offset1:12
	ds_read2st64_b32 v[74:75], v134 offset0:16 offset1:20
	ds_read2st64_b32 v[72:73], v134 offset0:24 offset1:28
	v_add_u32_e32 v130, 0xa500, v125
	ds_read2_b32 v[80:81], v130 offset1:1
	ds_read2_b32 v[104:105], v130 offset0:2 offset1:3
	ds_read2_b32 v[208:209], v130 offset0:16 offset1:17
	ds_read2_b32 v[210:211], v130 offset0:18 offset1:19
	ds_read2_b32 v[190:191], v106 offset0:192 offset1:196
	ds_read2_b32 v[192:193], v106 offset0:200 offset1:204
	ds_read2_b32 v[194:195], v106 offset0:208 offset1:212
	ds_read2_b32 v[196:197], v106 offset0:216 offset1:220
	ds_read2_b32 v[198:199], v128 offset0:208 offset1:212
	ds_read2_b32 v[200:201], v128 offset0:216 offset1:220
	ds_read2_b32 v[202:203], v128 offset0:224 offset1:228
	ds_read2_b32 v[204:205], v128 offset0:232 offset1:236
	s_waitcnt lgkmcnt(8)
	v_mul_f32_e32 v80, 0x3fb8aa3b, v80
	v_mul_f32_e32 v81, 0x3fb8aa3b, v81
	v_mul_f32_e32 v104, 0x3fb8aa3b, v104
	v_mul_f32_e32 v105, 0x3fb8aa3b, v105
	v_mul_f32_e32 v208, 0x3fb8aa3b, v208
	v_mul_f32_e32 v209, 0x3fb8aa3b, v209
	v_mul_f32_e32 v210, 0x3fb8aa3b, v210
	v_mul_f32_e32 v211, 0x3fb8aa3b, v211
	v_exp_f32_e32 v80, v80
	v_exp_f32_e32 v81, v81
	v_exp_f32_e32 v104, v104
	v_exp_f32_e32 v105, v105
	v_exp_f32_e32 v208, v208
	v_exp_f32_e32 v209, v209
	v_exp_f32_e32 v210, v210
	v_exp_f32_e32 v211, v211
	s_nop 0
	v_pk_mul_f32 v[100:101], v[64:65], v[80:81]
	v_pk_mul_f32 v[102:103], v[66:67], v[104:105]
	v_pk_mul_f32 v[212:213], v[68:69], v[208:209]
	v_pk_mul_f32 v[214:215], v[70:71], v[210:211]
	s_waitcnt lgkmcnt(3)
	v_mfma_f32_16x16x4_f32 v[100:103], v190, v78, v[100:103]
	v_mfma_f32_16x16x4_f32 v[212:215], v198, v78, v[212:215]
	v_mfma_f32_16x16x4_f32 v[100:103], v191, v79, v[100:103]
	v_mfma_f32_16x16x4_f32 v[212:215], v199, v79, v[212:215]
	s_waitcnt lgkmcnt(2)
	v_mfma_f32_16x16x4_f32 v[100:103], v192, v76, v[100:103]
	v_mfma_f32_16x16x4_f32 v[212:215], v200, v76, v[212:215]
	v_mfma_f32_16x16x4_f32 v[100:103], v193, v77, v[100:103]
	v_mfma_f32_16x16x4_f32 v[212:215], v201, v77, v[212:215]
	s_waitcnt lgkmcnt(1)
	v_mfma_f32_16x16x4_f32 v[100:103], v194, v74, v[100:103]
	v_mfma_f32_16x16x4_f32 v[212:215], v202, v74, v[212:215]
	v_mfma_f32_16x16x4_f32 v[100:103], v195, v75, v[100:103]
	v_mfma_f32_16x16x4_f32 v[212:215], v203, v75, v[212:215]
	s_waitcnt lgkmcnt(0)
	v_mfma_f32_16x16x4_f32 v[100:103], v196, v72, v[100:103]
	v_mfma_f32_16x16x4_f32 v[212:215], v204, v72, v[212:215]
	v_mfma_f32_16x16x4_f32 v[100:103], v197, v73, v[100:103]
	v_mfma_f32_16x16x4_f32 v[212:215], v205, v73, v[212:215]
	v_lshl_add_u64 v[80:81], s[40:41], 0, v[96:97]
	v_lshl_add_u64 v[104:105], s[40:41], 0, v[94:95]
	s_mov_b32 s0, 0x2ea00000
	v_add_co_u32_e32 v216, vcc, s0, v80
	s_nop 1
	v_addc_co_u32_e32 v217, vcc, 0, v81, vcc
	s_mov_b32 s0, 0x2ea01000
	v_add_co_u32_e32 v218, vcc, s0, v80
	s_nop 1
	v_addc_co_u32_e32 v219, vcc, 0, v81, vcc
	s_mov_b32 s0, 0x2ea03000
	v_add_co_u32_e32 v220, vcc, s0, v80
	s_nop 1
	v_addc_co_u32_e32 v221, vcc, 0, v81, vcc
	s_mov_b32 s0, 0x2ea04000
	v_add_co_u32_e32 v222, vcc, s0, v80
	s_nop 1
	v_addc_co_u32_e32 v223, vcc, 0, v81, vcc
	global_store_dword v[216:217], v100, off
	global_store_dword v[218:219], v101, off offset:2048
	global_store_dword v[220:221], v102, off
	global_store_dword v[222:223], v103, off offset:2048
	s_mov_b32 s0, 0x2ea18000
	v_add_co_u32_e32 v216, vcc, s0, v104
	s_nop 1
	v_addc_co_u32_e32 v217, vcc, 0, v105, vcc
	s_mov_b32 s0, 0x2ea19000
	v_add_co_u32_e32 v218, vcc, s0, v104
	s_nop 1
	v_addc_co_u32_e32 v219, vcc, 0, v105, vcc
	s_mov_b32 s0, 0x2ea1b000
	v_add_co_u32_e32 v220, vcc, s0, v104
	s_nop 1
	v_addc_co_u32_e32 v221, vcc, 0, v105, vcc
	s_mov_b32 s0, 0x2ea1c000
	v_add_co_u32_e32 v222, vcc, s0, v104
	s_nop 1
	v_addc_co_u32_e32 v223, vcc, 0, v105, vcc
	global_store_dword v[216:217], v212, off
	global_store_dword v[218:219], v213, off offset:2048
	global_store_dword v[220:221], v214, off
	global_store_dword v[222:223], v215, off offset:2048
	v_mov_b32_e32 v80, s78
	ds_read_b32 v80, v80 offset:42364
	ds_read_b32 v56, v135 offset:42368
	ds_read_b32 v57, v135 offset:42384
	ds_read_b32 v58, v135 offset:42400
	ds_read_b32 v59, v135 offset:42416
	ds_read_b32 v60, v135 offset:42432
	ds_read_b32 v61, v135 offset:42448
	ds_read_b32 v62, v135 offset:42464
	ds_read_b32 v63, v135 offset:42480
	ds_read_b32 v189, v148 offset:16896
	ds_read_b32 v190, v148 offset:19008
	ds_read_b32 v191, v148 offset:21120
	ds_read_b32 v192, v148 offset:23232
	ds_read_b32 v193, v148 offset:25344
	ds_read_b32 v194, v148 offset:27456
	s_waitcnt lgkmcnt(14)
	v_mul_f32_e32 v106, 0x3fb8aa3b, v80
	v_exp_f32_e32 v106, v106
	ds_read_b32 v195, v148 offset:29568
	ds_read_b32 v196, v148 offset:31680
	ds_read_b32 v197, v148 offset:16960
	ds_read_b32 v198, v148 offset:19072
	ds_read_b32 v199, v148 offset:21184
	ds_read_b32 v200, v148 offset:23296
	s_waitcnt lgkmcnt(12)
	v_pk_mul_f32 v[48:49], v[48:49], v[106:107] op_sel_hi:[1,0]
	v_pk_mul_f32 v[50:51], v[50:51], v[106:107] op_sel_hi:[1,0]
	ds_read_b32 v201, v148 offset:25408
	s_waitcnt lgkmcnt(12)
	v_mul_f32_e32 v205, v189, v56
	ds_read_b32 v202, v148 offset:27520
	s_waitcnt lgkmcnt(12)
	v_mul_f32_e32 v208, v190, v57
	v_mfma_f32_16x16x4_f32 v[48:51], v205, v78, v[48:51]
	ds_read_b32 v203, v148 offset:29632
	s_waitcnt lgkmcnt(12)
	v_mul_f32_e32 v205, v191, v58
	v_mfma_f32_16x16x4_f32 v[48:51], v208, v79, v[48:51]
	ds_read_b32 v204, v148 offset:31744
	s_waitcnt lgkmcnt(12)
; #define MFMA16F(a, b, c) __builtin_amdgcn_mfma_f32_16x16x4f32((a), (b), (c), 0, 0, 0)
; DI void gdn_scan_block(LAS unsigned char* lds, int c, const float* P, const GdnPar& pr, float* ORAW, int tid, int lane, int wave) {
;     ...
;             const float e31 = __expf(GC_[31]);
;             float ej[8];
; #pragma unroll
;             for (int js = 0; js < 8; ++js) ej[js] = E31_[4 * js + g];
; #pragma unroll
;             for (int kb8 = 0; kb8 < 8; ++kb8) { f32x4 acc = Sacc[kb8] * e31;
; #pragma unroll
;                 for (int js = 0; js < 8; ++js) acc = MFMA16F(K_[(4 * js + g) * KP + 16 * kb8 + m] * ej[js], bC[js], acc);
;                 Sacc[kb8] = acc; }
	v_mul_f32_e32 v208, v192, v59
	v_mfma_f32_16x16x4_f32 v[48:51], v205, v76, v[48:51]
	ds_read_b32 v189, v148 offset:17024
	s_waitcnt lgkmcnt(12)
	v_mul_f32_e32 v205, v193, v60
	v_mfma_f32_16x16x4_f32 v[48:51], v208, v77, v[48:51]
	ds_read_b32 v190, v148 offset:19136
	s_waitcnt lgkmcnt(12)
	v_mul_f32_e32 v208, v194, v61
	v_mfma_f32_16x16x4_f32 v[48:51], v205, v74, v[48:51]
	ds_read_b32 v191, v148 offset:21248
	s_waitcnt lgkmcnt(12)
	v_mul_f32_e32 v205, v195, v62
	v_mfma_f32_16x16x4_f32 v[48:51], v208, v75, v[48:51]
	ds_read_b32 v192, v148 offset:23360
	s_waitcnt lgkmcnt(12)
	v_mul_f32_e32 v208, v196, v63
	v_mfma_f32_16x16x4_f32 v[48:51], v205, v72, v[48:51]
	v_pk_mul_f32 v[24:25], v[24:25], v[106:107] op_sel_hi:[1,0]
	v_pk_mul_f32 v[26:27], v[26:27], v[106:107] op_sel_hi:[1,0]
	ds_read_b32 v193, v148 offset:25472
	s_waitcnt lgkmcnt(12)
	v_mul_f32_e32 v205, v197, v56
	v_mfma_f32_16x16x4_f32 v[48:51], v208, v73, v[48:51]
	ds_read_b32 v194, v148 offset:27584
	s_waitcnt lgkmcnt(12)
	v_mul_f32_e32 v208, v198, v57
	v_mfma_f32_16x16x4_f32 v[24:27], v205, v78, v[24:27]
	ds_read_b32 v195, v148 offset:29696
	s_waitcnt lgkmcnt(12)
	v_mul_f32_e32 v205, v199, v58
	v_mfma_f32_16x16x4_f32 v[24:27], v208, v79, v[24:27]
	ds_read_b32 v196, v148 offset:31808
	s_waitcnt lgkmcnt(12)
	v_mul_f32_e32 v208, v200, v59
	v_mfma_f32_16x16x4_f32 v[24:27], v205, v76, v[24:27]
	ds_read_b32 v197, v148 offset:17088
	s_waitcnt lgkmcnt(12)
	v_mul_f32_e32 v205, v201, v60
	v_mfma_f32_16x16x4_f32 v[24:27], v208, v77, v[24:27]
	ds_read_b32 v198, v148 offset:19200
	s_waitcnt lgkmcnt(12)
	v_mul_f32_e32 v208, v202, v61
	v_mfma_f32_16x16x4_f32 v[24:27], v205, v74, v[24:27]
	ds_read_b32 v199, v148 offset:21312
	s_waitcnt lgkmcnt(12)
	v_mul_f32_e32 v205, v203, v62
	v_mfma_f32_16x16x4_f32 v[24:27], v208, v75, v[24:27]
	ds_read_b32 v200, v148 offset:23424
	s_waitcnt lgkmcnt(12)
	v_mul_f32_e32 v208, v204, v63
	v_mfma_f32_16x16x4_f32 v[24:27], v205, v72, v[24:27]
	v_pk_mul_f32 v[36:37], v[36:37], v[106:107] op_sel_hi:[1,0]
	v_pk_mul_f32 v[38:39], v[38:39], v[106:107] op_sel_hi:[1,0]
	ds_read_b32 v201, v148 offset:25536
	s_waitcnt lgkmcnt(12)
	v_mul_f32_e32 v205, v189, v56
	v_mfma_f32_16x16x4_f32 v[24:27], v208, v73, v[24:27]
	ds_read_b32 v202, v148 offset:27648
	s_waitcnt lgkmcnt(12)
	v_mul_f32_e32 v208, v190, v57
	v_mfma_f32_16x16x4_f32 v[36:39], v205, v78, v[36:39]
	ds_read_b32 v203, v148 offset:29760
	s_waitcnt lgkmcnt(12)
	v_mul_f32_e32 v205, v191, v58
	v_mfma_f32_16x16x4_f32 v[36:39], v208, v79, v[36:39]
	ds_read_b32 v204, v148 offset:31872
	s_waitcnt lgkmcnt(12)
	v_mul_f32_e32 v208, v192, v59
	v_mfma_f32_16x16x4_f32 v[36:39], v205, v76, v[36:39]
	ds_read_b32 v189, v148 offset:17152
	s_waitcnt lgkmcnt(12)
	v_mul_f32_e32 v205, v193, v60
	v_mfma_f32_16x16x4_f32 v[36:39], v208, v77, v[36:39]
	ds_read_b32 v190, v148 offset:19264
	s_waitcnt lgkmcnt(12)
	v_mul_f32_e32 v208, v194, v61
	v_mfma_f32_16x16x4_f32 v[36:39], v205, v74, v[36:39]
	ds_read_b32 v191, v148 offset:21376
	s_waitcnt lgkmcnt(12)
	v_mul_f32_e32 v205, v195, v62
	v_mfma_f32_16x16x4_f32 v[36:39], v208, v75, v[36:39]
	ds_read_b32 v192, v148 offset:23488
	s_waitcnt lgkmcnt(12)
	v_mul_f32_e32 v208, v196, v63
	v_mfma_f32_16x16x4_f32 v[36:39], v205, v72, v[36:39]
	v_pk_mul_f32 v[28:29], v[28:29], v[106:107] op_sel_hi:[1,0]
	v_pk_mul_f32 v[30:31], v[30:31], v[106:107] op_sel_hi:[1,0]
	ds_read_b32 v193, v148 offset:25600
	s_waitcnt lgkmcnt(12)
	v_mul_f32_e32 v205, v197, v56
	v_mfma_f32_16x16x4_f32 v[36:39], v208, v73, v[36:39]
	ds_read_b32 v194, v148 offset:27712
	s_waitcnt lgkmcnt(12)
	v_mul_f32_e32 v208, v198, v57
	v_mfma_f32_16x16x4_f32 v[28:31], v205, v78, v[28:31]
	ds_read_b32 v195, v148 offset:29824
	s_waitcnt lgkmcnt(12)
	v_mul_f32_e32 v205, v199, v58
	v_mfma_f32_16x16x4_f32 v[28:31], v208, v79, v[28:31]
	ds_read_b32 v196, v148 offset:31936
	s_waitcnt lgkmcnt(12)
	v_mul_f32_e32 v208, v200, v59
	v_mfma_f32_16x16x4_f32 v[28:31], v205, v76, v[28:31]
	ds_read_b32 v197, v148 offset:17216
	s_waitcnt lgkmcnt(12)
	v_mul_f32_e32 v205, v201, v60
	v_mfma_f32_16x16x4_f32 v[28:31], v208, v77, v[28:31]
	ds_read_b32 v198, v148 offset:19328
	s_waitcnt lgkmcnt(12)
	v_mul_f32_e32 v208, v202, v61
	v_mfma_f32_16x16x4_f32 v[28:31], v205, v74, v[28:31]
	ds_read_b32 v199, v148 offset:21440
	s_waitcnt lgkmcnt(12)
	v_mul_f32_e32 v205, v203, v62
	v_mfma_f32_16x16x4_f32 v[28:31], v208, v75, v[28:31]
	ds_read_b32 v200, v148 offset:23552
	s_waitcnt lgkmcnt(12)
	v_mul_f32_e32 v208, v204, v63
	v_mfma_f32_16x16x4_f32 v[28:31], v205, v72, v[28:31]
	v_pk_mul_f32 v[40:41], v[40:41], v[106:107] op_sel_hi:[1,0]
	v_pk_mul_f32 v[42:43], v[42:43], v[106:107] op_sel_hi:[1,0]
	ds_read_b32 v201, v148 offset:25664
	s_waitcnt lgkmcnt(12)
; #define MFMA16F(a, b, c) __builtin_amdgcn_mfma_f32_16x16x4f32((a), (b), (c), 0, 0, 0)
; DI void gdn_scan_block(LAS unsigned char* lds, int c, const float* P, const GdnPar& pr, float* ORAW, int tid, int lane, int wave) {
;     ...
;             const float e31 = __expf(GC_[31]);
;             float ej[8];
; #pragma unroll
;             for (int js = 0; js < 8; ++js) ej[js] = E31_[4 * js + g];
; #pragma unroll
;             for (int kb8 = 0; kb8 < 8; ++kb8) { f32x4 acc = Sacc[kb8] * e31;
; #pragma unroll
;                 for (int js = 0; js < 8; ++js) acc = MFMA16F(K_[(4 * js + g) * KP + 16 * kb8 + m] * ej[js], bC[js], acc);
;                 Sacc[kb8] = acc; }
	v_mul_f32_e32 v205, v189, v56
	v_mfma_f32_16x16x4_f32 v[28:31], v208, v73, v[28:31]
	ds_read_b32 v202, v148 offset:27776
	s_waitcnt lgkmcnt(12)
	v_mul_f32_e32 v208, v190, v57
	v_mfma_f32_16x16x4_f32 v[40:43], v205, v78, v[40:43]
	ds_read_b32 v203, v148 offset:29888
	s_waitcnt lgkmcnt(12)
	v_mul_f32_e32 v205, v191, v58
	v_mfma_f32_16x16x4_f32 v[40:43], v208, v79, v[40:43]
	ds_read_b32 v204, v148 offset:32000
	s_waitcnt lgkmcnt(12)
	v_mul_f32_e32 v208, v192, v59
	v_mfma_f32_16x16x4_f32 v[40:43], v205, v76, v[40:43]
	ds_read_b32 v189, v148 offset:17280
	s_waitcnt lgkmcnt(12)
	v_mul_f32_e32 v205, v193, v60
	v_mfma_f32_16x16x4_f32 v[40:43], v208, v77, v[40:43]
	ds_read_b32 v190, v148 offset:19392
	s_waitcnt lgkmcnt(12)
	v_mul_f32_e32 v208, v194, v61
	v_mfma_f32_16x16x4_f32 v[40:43], v205, v74, v[40:43]
	ds_read_b32 v191, v148 offset:21504
	s_waitcnt lgkmcnt(12)
	v_mul_f32_e32 v205, v195, v62
	v_mfma_f32_16x16x4_f32 v[40:43], v208, v75, v[40:43]
	ds_read_b32 v192, v148 offset:23616
	s_waitcnt lgkmcnt(12)
	v_mul_f32_e32 v208, v196, v63
	v_mfma_f32_16x16x4_f32 v[40:43], v205, v72, v[40:43]
	v_pk_mul_f32 v[32:33], v[32:33], v[106:107] op_sel_hi:[1,0]
	v_pk_mul_f32 v[34:35], v[34:35], v[106:107] op_sel_hi:[1,0]
	ds_read_b32 v193, v148 offset:25728
	s_waitcnt lgkmcnt(12)
	v_mul_f32_e32 v205, v197, v56
	v_mfma_f32_16x16x4_f32 v[40:43], v208, v73, v[40:43]
	ds_read_b32 v194, v148 offset:27840
	s_waitcnt lgkmcnt(12)
	v_mul_f32_e32 v208, v198, v57
	v_mfma_f32_16x16x4_f32 v[32:35], v205, v78, v[32:35]
	ds_read_b32 v195, v148 offset:29952
	s_waitcnt lgkmcnt(12)
	v_mul_f32_e32 v205, v199, v58
	v_mfma_f32_16x16x4_f32 v[32:35], v208, v79, v[32:35]
	ds_read_b32 v196, v148 offset:32064
	s_waitcnt lgkmcnt(12)
	v_mul_f32_e32 v208, v200, v59
	v_mfma_f32_16x16x4_f32 v[32:35], v205, v76, v[32:35]
	ds_read_b32 v197, v148 offset:17344
	s_waitcnt lgkmcnt(12)
	v_mul_f32_e32 v205, v201, v60
	v_mfma_f32_16x16x4_f32 v[32:35], v208, v77, v[32:35]
	ds_read_b32 v198, v148 offset:19456
	s_waitcnt lgkmcnt(12)
	v_mul_f32_e32 v208, v202, v61
	v_mfma_f32_16x16x4_f32 v[32:35], v205, v74, v[32:35]
	ds_read_b32 v199, v148 offset:21568
	s_waitcnt lgkmcnt(12)
	v_mul_f32_e32 v205, v203, v62
	v_mfma_f32_16x16x4_f32 v[32:35], v208, v75, v[32:35]
	ds_read_b32 v200, v148 offset:23680
	s_waitcnt lgkmcnt(12)
	v_mul_f32_e32 v208, v204, v63
	v_mfma_f32_16x16x4_f32 v[32:35], v205, v72, v[32:35]
	v_pk_mul_f32 v[44:45], v[44:45], v[106:107] op_sel_hi:[1,0]
	v_pk_mul_f32 v[46:47], v[46:47], v[106:107] op_sel_hi:[1,0]
	ds_read_b32 v201, v148 offset:25792
	s_waitcnt lgkmcnt(12)
	v_mul_f32_e32 v205, v189, v56
	v_mfma_f32_16x16x4_f32 v[32:35], v208, v73, v[32:35]
	ds_read_b32 v202, v148 offset:27904
	s_waitcnt lgkmcnt(12)
	v_mul_f32_e32 v208, v190, v57
	v_mfma_f32_16x16x4_f32 v[44:47], v205, v78, v[44:47]
	ds_read_b32 v203, v148 offset:30016
	s_waitcnt lgkmcnt(12)
	v_mul_f32_e32 v205, v191, v58
	v_mfma_f32_16x16x4_f32 v[44:47], v208, v79, v[44:47]
	ds_read_b32 v204, v148 offset:32128
	s_waitcnt lgkmcnt(12)
	v_mul_f32_e32 v208, v192, v59
	v_mfma_f32_16x16x4_f32 v[44:47], v205, v76, v[44:47]
	s_waitcnt lgkmcnt(11)
	v_mul_f32_e32 v205, v193, v60
	v_mfma_f32_16x16x4_f32 v[44:47], v208, v77, v[44:47]
	s_waitcnt lgkmcnt(10)
	v_mul_f32_e32 v208, v194, v61
	v_mfma_f32_16x16x4_f32 v[44:47], v205, v74, v[44:47]
	s_waitcnt lgkmcnt(9)
	v_mul_f32_e32 v205, v195, v62
	v_mfma_f32_16x16x4_f32 v[44:47], v208, v75, v[44:47]
	s_waitcnt lgkmcnt(8)
	v_mul_f32_e32 v208, v196, v63
	v_mfma_f32_16x16x4_f32 v[44:47], v205, v72, v[44:47]
	v_pk_mul_f32 v[52:53], v[52:53], v[106:107] op_sel_hi:[1,0]
	v_pk_mul_f32 v[54:55], v[54:55], v[106:107] op_sel_hi:[1,0]
	s_waitcnt lgkmcnt(7)
	v_mul_f32_e32 v205, v197, v56
	v_mfma_f32_16x16x4_f32 v[44:47], v208, v73, v[44:47]
	s_waitcnt lgkmcnt(6)
	v_mul_f32_e32 v208, v198, v57
	v_mfma_f32_16x16x4_f32 v[52:55], v205, v78, v[52:55]
	s_waitcnt lgkmcnt(5)
	v_mul_f32_e32 v205, v199, v58
	v_mfma_f32_16x16x4_f32 v[52:55], v208, v79, v[52:55]
	s_waitcnt lgkmcnt(4)
	v_mul_f32_e32 v208, v200, v59
	v_mfma_f32_16x16x4_f32 v[52:55], v205, v76, v[52:55]
	s_waitcnt lgkmcnt(3)
	v_mul_f32_e32 v205, v201, v60
	v_mfma_f32_16x16x4_f32 v[52:55], v208, v77, v[52:55]
	s_waitcnt lgkmcnt(2)
	v_mul_f32_e32 v208, v202, v61
	v_mfma_f32_16x16x4_f32 v[52:55], v205, v74, v[52:55]
	s_waitcnt lgkmcnt(1)
	v_mul_f32_e32 v205, v203, v62
	v_mfma_f32_16x16x4_f32 v[52:55], v208, v75, v[52:55]
	s_waitcnt lgkmcnt(0)
	v_mul_f32_e32 v208, v204, v63
	v_mfma_f32_16x16x4_f32 v[52:55], v205, v72, v[52:55]
	s_nop 1
	v_mfma_f32_16x16x4_f32 v[52:55], v208, v73, v[52:55]
